# plus attention: the 16 packed v_pk_mul_f32 of the O rescale split into plain v_mul_f32 (bit-identical)
# speedup vs baseline: 1.0008x; 1.0005x over previous
.LBB0_291:
	s_or_b64 exec, exec, s[36:37]
	s_mul_hi_u32 s36, s54, 0xaaaaaaab
	s_lshr_b32 s36, s36, 2
	s_mul_i32 s36, s36, 0x18000
	v_subrev_u32_e32 v178, s36, v164
	v_subrev_u32_e32 v179, s36, v166
	v_subrev_u32_e32 v1, s36, v168
	v_subrev_u32_e32 v2, s36, v169
	v_subrev_u32_e32 v182, s36, v170
	v_subrev_u32_e32 v184, s36, v172
	v_subrev_u32_e32 v180, s36, v173
	v_subrev_u32_e32 v181, s36, v175
	v_subrev_u32_e32 v0, s36, v129
	v_subrev_u32_e32 v6, s36, v128
	v_subrev_u32_e32 v8, s36, v115
	v_subrev_u32_e32 v7, s36, v127
	s_barrier
	v_cmp_ge_i32_e32 vcc, s54, v123
	s_or_b64 s[36:37], s[48:49], vcc
	s_and_saveexec_b64 s[44:45], s[36:37]
	s_xor_b64 s[36:37], exec, s[44:45]
	s_cbranch_execz .LBB0_295
	v_add_u32_e32 v5, s53, v163
	v_add_u32_e32 v4, v5, v8
	ds_read_b128 v[8:11], v4
	v_add_u32_e32 v0, v5, v0
	s_waitcnt lgkmcnt(0)
	v_mfma_f32_32x32x16_f16 v[48:63], v[8:11], v[88:91], 0
	ds_read_b128 v[8:11], v4 offset:4096
	v_add_u32_e32 v4, v5, v7
	s_waitcnt lgkmcnt(0)
	v_mfma_f32_32x32x16_f16 v[64:79], v[8:11], v[88:91], 0
	ds_read_b128 v[8:11], v4
	s_waitcnt lgkmcnt(0)
	v_mfma_f32_32x32x16_f16 v[48:63], v[8:11], v[80:83], v[48:63]
	ds_read_b128 v[8:11], v4 offset:4096
	v_add_u32_e32 v4, v5, v6
	s_waitcnt lgkmcnt(0)
	v_mfma_f32_32x32x16_f16 v[64:79], v[8:11], v[80:83], v[64:79]
	ds_read_b128 v[6:9], v4
	s_waitcnt lgkmcnt(0)
	v_mfma_f32_32x32x16_f16 v[48:63], v[6:9], v[84:87], v[48:63]
	ds_read_b128 v[6:9], v4 offset:4096
	s_waitcnt lgkmcnt(0)
	v_mfma_f32_32x32x16_f16 v[64:79], v[6:9], v[84:87], v[64:79]
	ds_read_b128 v[6:9], v0
	s_waitcnt lgkmcnt(0)
	v_mfma_f32_32x32x16_f16 v[48:63], v[6:9], v[92:95], v[48:63]
	ds_read_b128 v[6:9], v0 offset:4096
	s_waitcnt lgkmcnt(0)
	v_mfma_f32_32x32x16_f16 v[64:79], v[6:9], v[92:95], v[64:79]
	s_nop 11
	v_max3_f32 v0, v48, s55, v64
	v_max3_f32 v0, v0, v49, v65
	v_max3_f32 v0, v0, v50, v66
	v_max3_f32 v0, v0, v51, v67
	v_max3_f32 v0, v0, v52, v68
	v_max3_f32 v0, v0, v53, v69
	v_max3_f32 v0, v0, v54, v70
	v_max3_f32 v0, v0, v55, v71
	v_max3_f32 v0, v0, v56, v72
	v_max3_f32 v0, v0, v57, v73
	v_max3_f32 v0, v0, v58, v74
	v_max3_f32 v0, v0, v59, v75
	v_max3_f32 v0, v0, v60, v76
	v_max3_f32 v0, v0, v61, v77
	v_max3_f32 v0, v0, v62, v78
	v_max3_f32 v0, v0, v63, v79
	v_mov_b32_e32 v4, v0
	s_nop 1
	v_permlane32_swap_b32_e32 v0, v4
	v_max3_f32 v4, v186, v0, v4
	v_sub_f32_e32 v0, v186, v4
	v_exp_f32_e32 v0, v0
	s_nop 0
	v_cmp_neq_f32_e32 vcc, 1.0, v0
	s_cbranch_vccz .LBB0_294
	v_mul_f32_e32 v30, v0, v30
	v_mul_f32_e32 v31, v0, v31
	v_mul_f32_e32 v28, v0, v28
	v_mul_f32_e32 v29, v0, v29
	v_mul_f32_e32 v26, v0, v26
	v_mul_f32_e32 v27, v0, v27
	v_mul_f32_e32 v24, v0, v24
	v_mul_f32_e32 v25, v0, v25
	v_mul_f32_e32 v22, v0, v22
	v_mul_f32_e32 v23, v0, v23
	v_mul_f32_e32 v20, v0, v20
	v_mul_f32_e32 v21, v0, v21
	v_mul_f32_e32 v18, v0, v18
	v_mul_f32_e32 v19, v0, v19
	v_mul_f32_e32 v16, v0, v16
	v_mul_f32_e32 v17, v0, v17
	v_mul_f32_e32 v46, v0, v46
	v_mul_f32_e32 v47, v0, v47
	v_mul_f32_e32 v44, v0, v44
	v_mul_f32_e32 v45, v0, v45
	v_mul_f32_e32 v42, v0, v42
	v_mul_f32_e32 v43, v0, v43
	v_mul_f32_e32 v40, v0, v40
	v_mul_f32_e32 v41, v0, v41
	v_mul_f32_e32 v38, v0, v38
	v_mul_f32_e32 v39, v0, v39
	v_mul_f32_e32 v36, v0, v36
	v_mul_f32_e32 v37, v0, v37
	v_mul_f32_e32 v34, v0, v34
	v_mul_f32_e32 v35, v0, v35
	v_mul_f32_e32 v32, v0, v32
	v_mul_f32_e32 v33, v0, v33

.LBB0_295:
	s_andn2_saveexec_b64 s[36:37], s[36:37]
	s_cbranch_execz .LBB0_263
	v_add_u32_e32 v4, s54, v120
	v_cmp_ge_u32_e32 vcc, v4, v122
	v_cmp_le_u32_e64 s[44:45], v4, v130
	s_and_b64 s[50:51], vcc, s[44:45]
	s_and_saveexec_b64 s[44:45], s[50:51]
	s_cbranch_execz .LBB0_262
	v_add_u32_e32 v185, s53, v163
	v_add_u32_e32 v4, v185, v8
	ds_read_b128 v[64:67], v4
	ds_read_b128 v[68:71], v4 offset:4096
	v_add_u32_e32 v4, v185, v7
	ds_read_b128 v[96:99], v4
	ds_read_b128 v[104:107], v4 offset:4096
	v_add_u32_e32 v4, v185, v6
	v_add_u32_e32 v0, v185, v0
	ds_read_b128 v[12:15], v4
	ds_read_b128 v[100:103], v4 offset:4096
	ds_read_b128 v[4:7], v0
	ds_read_b128 v[8:11], v0 offset:4096
	v_add_u32_e32 v193, 16, v149
	v_add_u32_e32 v190, 16, v147
	v_add_u32_e32 v191, 16, v145
	v_add_u32_e32 v192, 16, v143
	v_add_u32_e32 v189, 16, v134
	v_add_u32_e32 v188, 16, v133
	v_add_u32_e32 v187, 16, v132
	v_add_u32_e32 v0, 16, v131
	s_and_saveexec_b64 s[50:51], s[42:43]
	s_xor_b64 s[50:51], exec, s[50:51]
	s_cbranch_execz .LBB0_301
	s_waitcnt lgkmcnt(0)
	v_mfma_f32_32x32x16_f16 v[48:63], v[68:71], v[88:91], 0
	v_add_u32_e32 v68, 16, v154
	v_add_u32_e32 v69, 16, v153
	v_add_u32_e32 v70, 16, v152
	v_add_u32_e32 v71, 16, v151
	v_mfma_f32_32x32x16_f16 v[48:63], v[104:107], v[80:83], v[48:63]
	v_add_u32_e32 v106, 16, v156
	v_add_u32_e32 v107, 16, v155
	v_mfma_f32_32x32x16_f16 v[48:63], v[100:103], v[84:87], v[48:63]
	v_add_u32_e32 v101, 16, v162
	v_mfma_f32_32x32x16_f16 v[48:63], v[8:11], v[92:95], v[48:63]
	ds_read_b32 v8, v193
	ds_read_b32 v9, v190
	ds_read_b32 v11, v191
	ds_read_b32 v72, v192
	ds_read_b32 v102, v68
	ds_read_b32 v103, v69
	ds_read_b32 v104, v70
	ds_read_b32 v105, v71
	s_waitcnt lgkmcnt(0)
	s_nop 2
	v_add_f32_e32 v100, v48, v8
	v_add_f32_e32 v8, v51, v72
	v_mfma_f32_32x32x16_f16 v[64:79], v[64:67], v[88:91], 0
	v_add_f32_e32 v10, v49, v9
	v_add_f32_e32 v9, v50, v11
	v_add_u32_e32 v11, 16, v161
	v_add_u32_e32 v48, 16, v160
	v_add_u32_e32 v49, 16, v159
	v_add_u32_e32 v50, 16, v158
	v_add_u32_e32 v51, 16, v157
	v_mfma_f32_32x32x16_f16 v[64:79], v[96:99], v[80:83], v[64:79]
	ds_read_b32 v96, v101
	ds_read_b32 v11, v11
	ds_read_b32 v48, v48
	ds_read_b32 v49, v49
	ds_read_b32 v50, v50
	ds_read_b32 v98, v51
	ds_read_b32 v99, v106
	ds_read_b32 v101, v107
	s_waitcnt lgkmcnt(0)
	v_add_f32_e32 v97, v52, v96
	v_add_f32_e32 v96, v53, v11
	v_add_f32_e32 v53, v54, v48
	v_add_f32_e32 v52, v55, v49
	v_add_f32_e32 v51, v56, v50
	v_add_f32_e32 v50, v57, v98
	v_mfma_f32_32x32x16_f16 v[64:79], v[12:15], v[84:87], v[64:79]
	ds_read_b32 v11, v189
	ds_read_b32 v12, v188
	ds_read_b32 v48, v187
	ds_read_b32 v0, v0
	v_add_f32_e32 v15, v58, v99
	v_add_f32_e32 v14, v59, v101
	v_add_f32_e32 v13, v60, v102
	v_mfma_f32_32x32x16_f16 v[64:79], v[4:7], v[92:95], v[64:79]
	v_add_f32_e32 v6, v62, v104
	v_add_f32_e32 v4, v63, v105
	s_waitcnt lgkmcnt(0)
	s_nop 8
	v_add_f32_e32 v5, v79, v0
	v_max3_f32 v0, v100, s55, v10
	v_max3_f32 v0, v0, v9, v8
	v_max3_f32 v0, v0, v97, v96
	v_max3_f32 v0, v0, v53, v52
	v_max3_f32 v0, v0, v51, v50
	v_add_f32_e32 v49, v76, v11
	v_max3_f32 v0, v0, v15, v14
	v_add_f32_e32 v12, v77, v12
	v_add_f32_e32 v11, v61, v103
	v_max3_f32 v0, v0, v49, v13
	v_add_f32_e32 v7, v78, v48
	v_max3_f32 v0, v0, v12, v11
	v_max3_f32 v0, v0, v7, v6
	v_max3_f32 v0, v0, v5, v4
	v_mov_b32_e32 v48, v0
	s_nop 1
	v_permlane32_swap_b32_e32 v0, v48
	v_max3_f32 v48, v186, v0, v48
	v_sub_f32_e32 v0, v186, v48
	v_exp_f32_e32 v0, v0
	s_nop 0
	v_cmp_neq_f32_e32 vcc, 1.0, v0
	s_cbranch_vccz .LBB0_300
	v_mul_f32_e32 v30, v0, v30
	v_mul_f32_e32 v31, v0, v31
	v_mul_f32_e32 v28, v0, v28
	v_mul_f32_e32 v29, v0, v29
	v_mul_f32_e32 v26, v0, v26
	v_mul_f32_e32 v27, v0, v27
	v_mul_f32_e32 v24, v0, v24
	v_mul_f32_e32 v25, v0, v25
	v_mul_f32_e32 v22, v0, v22
	v_mul_f32_e32 v23, v0, v23
	v_mul_f32_e32 v20, v0, v20
	v_mul_f32_e32 v21, v0, v21
	v_mul_f32_e32 v18, v0, v18
	v_mul_f32_e32 v19, v0, v19
	v_mul_f32_e32 v16, v0, v16
	v_mul_f32_e32 v17, v0, v17
	v_mul_f32_e32 v46, v0, v46
	v_mul_f32_e32 v47, v0, v47
	v_mul_f32_e32 v44, v0, v44
	v_mul_f32_e32 v45, v0, v45
	v_mul_f32_e32 v42, v0, v42
	v_mul_f32_e32 v43, v0, v43
	v_mul_f32_e32 v40, v0, v40
	v_mul_f32_e32 v41, v0, v41
	v_mul_f32_e32 v38, v0, v38
	v_mul_f32_e32 v39, v0, v39
	v_mul_f32_e32 v36, v0, v36
	v_mul_f32_e32 v37, v0, v37
	v_mul_f32_e32 v34, v0, v34
	v_mul_f32_e32 v35, v0, v35
	v_mul_f32_e32 v32, v0, v32
	v_mul_f32_e32 v33, v0, v33

.LBB0_301:
	s_andn2_saveexec_b64 s[50:51], s[50:51]
	s_cbranch_execz .LBB0_261
	s_waitcnt lgkmcnt(0)
	v_mfma_f32_32x32x16_f16 v[48:63], v[64:67], v[88:91], 0
	v_mfma_f32_32x32x16_f16 v[64:79], v[68:71], v[88:91], 0
	v_mfma_f32_32x32x16_f16 v[48:63], v[96:99], v[80:83], v[48:63]
	v_add_u32_e32 v96, 16, v150
	v_add_u32_e32 v97, 16, v141
	v_add_u32_e32 v98, 16, v140
	v_add_u32_e32 v99, 16, v139
	v_mfma_f32_32x32x16_f16 v[64:79], v[104:107], v[80:83], v[64:79]
	v_mfma_f32_32x32x16_f16 v[48:63], v[12:15], v[84:87], v[48:63]
	v_add_u32_e32 v12, 16, v148
	v_add_u32_e32 v13, 16, v146
	v_add_u32_e32 v14, 16, v144
	v_add_u32_e32 v15, 16, v142
	v_mfma_f32_32x32x16_f16 v[64:79], v[100:103], v[84:87], v[64:79]
	v_mfma_f32_32x32x16_f16 v[48:63], v[4:7], v[92:95], v[48:63]
	ds_read_b32 v4, v96
	ds_read_b32 v5, v12
	ds_read_b32 v6, v13
	ds_read_b32 v7, v14
	ds_read_b32 v12, v15
	ds_read_b32 v13, v97
	ds_read_b32 v97, v98
	ds_read_b32 v98, v99
	v_add_u32_e32 v14, 16, v137
	v_add_u32_e32 v15, 16, v136
	s_waitcnt lgkmcnt(0)
	s_nop 0
	v_add_f32_e32 v96, v48, v4
	v_mfma_f32_32x32x16_f16 v[64:79], v[8:11], v[92:95], v[64:79]
	v_add_u32_e32 v4, 16, v138
	v_add_u32_e32 v48, 16, v135
	ds_read_b32 v99, v193
	ds_read_b32 v100, v190
	ds_read_b32 v101, v191
	ds_read_b32 v102, v192
	ds_read_b32 v4, v4
	ds_read_b32 v103, v14
	ds_read_b32 v104, v15
	ds_read_b32 v48, v48
	s_nop 1
	v_add_f32_e32 v69, v49, v5
	s_waitcnt lgkmcnt(0)
	v_add_f32_e32 v11, v56, v4
	v_add_f32_e32 v15, v52, v12
	v_add_f32_e32 v14, v53, v13
	v_add_f32_e32 v68, v65, v100
	v_add_f32_e32 v65, v50, v6
	v_add_f32_e32 v50, v51, v7
	ds_read_b32 v4, v189
	ds_read_b32 v5, v188
	ds_read_b32 v51, v187
	ds_read_b32 v0, v0
	v_add_f32_e32 v70, v64, v99
	s_waitcnt lgkmcnt(0)
	v_add_f32_e32 v7, v60, v4
	v_add_f32_e32 v64, v66, v101
	v_add_f32_e32 v49, v67, v102
	v_add_f32_e32 v4, v63, v0
	v_max3_f32 v0, v96, s55, v70
	v_max3_f32 v0, v0, v69, v68
	v_max3_f32 v0, v0, v65, v64
	v_max3_f32 v0, v0, v50, v49
	v_add_f32_e32 v13, v54, v97
	v_add_f32_e32 v12, v55, v98
	v_max3_f32 v0, v0, v15, v14
	v_add_f32_e32 v10, v57, v103
	v_max3_f32 v0, v0, v13, v12
	v_add_f32_e32 v9, v58, v104
	v_add_f32_e32 v8, v59, v48
	v_max3_f32 v0, v0, v11, v10
	v_add_f32_e32 v6, v61, v5
	v_max3_f32 v0, v0, v9, v8
	v_add_f32_e32 v5, v62, v51
	v_max3_f32 v0, v0, v7, v6
	v_max3_f32 v0, v0, v5, v4
	v_mov_b32_e32 v48, v0
	s_nop 1
	v_permlane32_swap_b32_e32 v0, v48
	v_max3_f32 v48, v186, v0, v48
	v_sub_f32_e32 v0, v186, v48
	v_exp_f32_e32 v0, v0
	s_nop 0
	v_cmp_neq_f32_e32 vcc, 1.0, v0
	s_cbranch_vccz .LBB0_260
	v_mul_f32_e32 v30, v0, v30
	v_mul_f32_e32 v31, v0, v31
	v_mul_f32_e32 v28, v0, v28
	v_mul_f32_e32 v29, v0, v29
	v_mul_f32_e32 v26, v0, v26
	v_mul_f32_e32 v27, v0, v27
	v_mul_f32_e32 v24, v0, v24
	v_mul_f32_e32 v25, v0, v25
	v_mul_f32_e32 v22, v0, v22
	v_mul_f32_e32 v23, v0, v23
	v_mul_f32_e32 v20, v0, v20
	v_mul_f32_e32 v21, v0, v21
	v_mul_f32_e32 v18, v0, v18
	v_mul_f32_e32 v19, v0, v19
	v_mul_f32_e32 v16, v0, v16
	v_mul_f32_e32 v17, v0, v17
	v_mul_f32_e32 v46, v0, v46
	v_mul_f32_e32 v47, v0, v47
	v_mul_f32_e32 v44, v0, v44
	v_mul_f32_e32 v45, v0, v45
	v_mul_f32_e32 v42, v0, v42
	v_mul_f32_e32 v43, v0, v43
	v_mul_f32_e32 v40, v0, v40
	v_mul_f32_e32 v41, v0, v41
	v_mul_f32_e32 v38, v0, v38
	v_mul_f32_e32 v39, v0, v39
	v_mul_f32_e32 v36, v0, v36
	v_mul_f32_e32 v37, v0, v37
	v_mul_f32_e32 v34, v0, v34
	v_mul_f32_e32 v35, v0, v35
	v_mul_f32_e32 v32, v0, v32
	v_mul_f32_e32 v33, v0, v33
	s_branch .LBB0_260
